# v39 + no lgkmcnt(0) between the same-wave LDS staging writes and reads in the DFT stage-1 store tails (LDS ops of one wave execute in order)
# speedup vs baseline: 1.0045x; 1.0045x over previous
.LBB0_129:
	v_add_u32_e32 v0, 0x800, v202
	s_waitcnt vmcnt(0)
	ds_write2_b64 v202, v[100:101], v[106:107] offset1:72
	ds_write2_b64 v202, v[108:109], v[116:117] offset0:144 offset1:216
	ds_write2_b64 v0, v[114:115], v[124:125] offset0:32 offset1:104
	ds_write2_b64 v0, v[126:127], v[134:135] offset0:176 offset1:248
	v_add_u32_e32 v0, 0x1000, v202
	ds_write2_b64 v0, v[118:119], v[132:133] offset0:64 offset1:136
	v_add_u32_e32 v0, 0x1400, v202
	ds_write2_b64 v0, v[128:129], v[142:143] offset0:80 offset1:152
	v_add_u32_e32 v0, 0x1800, v202
	ds_write2_b64 v0, v[130:131], v[144:145] offset0:96 offset1:168
	v_add_u32_e32 v0, 0x1c00, v202
	ds_write2_b64 v0, v[136:137], v[146:147] offset0:112 offset1:184
	v_add_u32_e32 v0, 0x2000, v202
	ds_write2_b64 v0, v[164:165], v[166:167] offset0:128 offset1:200
	v_add_u32_e32 v0, 0x2800, v202
	s_add_i32 s13, s6, s28
	ds_write2_b64 v0, v[160:161], v[162:163] offset0:16 offset1:88
	ds_write2_b64 v0, v[156:157], v[158:159] offset0:160 offset1:232
	v_add_u32_e32 v0, 0x3000, v202
	s_cmpk_lt_i32 s13, 0x1000
	ds_write2_b64 v0, v[148:149], v[150:151] offset0:48 offset1:120
	v_add_u32_e32 v0, 0x3400, v202
	s_cselect_b32 s7, s13, s6
	ds_write2_b64 v0, v[138:139], v[140:141] offset0:64 offset1:136
	v_add_u32_e32 v0, 0x3800, v202
	s_lshl_b32 s9, s7, 2
	ds_write2_b64 v0, v[120:121], v[122:123] offset0:80 offset1:152
	v_add_u32_e32 v0, 0x3c00, v202
	s_bfe_u32 s8, s7, 0x70004
	s_and_b32 s9, s9, 0xffffe000
	ds_write2_b64 v0, v[110:111], v[112:113] offset0:96 offset1:168
	v_add_u32_e32 v0, 0x4000, v202
	s_or_b32 s9, s9, s8
	ds_write2_b64 v0, v[102:103], v[104:105] offset0:112 offset1:184
	s_lshl_b32 s7, s7, 7
	v_or_b32_e32 v2, s9, v178
	v_mov_b64_e32 v[0:1], s[92:93]
	s_and_b32 s10, s7, 0x780
	v_mad_i64_i32 v[2:3], s[24:25], v2, s33, v[0:1]
	s_mov_b32 s11, s96
	v_lshl_add_u64 v[2:3], v[2:3], 0, s[10:11]
	v_or_b32_e32 v4, s9, v179
	v_lshl_add_u64 v[2:3], v[2:3], 0, v[154:155]
	v_mad_i64_i32 v[4:5], s[24:25], v4, s33, v[0:1]
	v_add_co_u32_e32 v2, vcc, s46, v2
	v_lshl_add_u64 v[4:5], v[4:5], 0, s[10:11]
	v_or_b32_e32 v6, s9, v180
	v_addc_co_u32_e32 v3, vcc, 0, v3, vcc
	v_lshl_add_u64 v[4:5], v[4:5], 0, v[154:155]
	v_mad_i64_i32 v[6:7], s[24:25], v6, s33, v[0:1]
	v_add_co_u32_e32 v4, vcc, s46, v4
	v_lshl_add_u64 v[6:7], v[6:7], 0, s[10:11]
	v_or_b32_e32 v8, s9, v181
	v_addc_co_u32_e32 v5, vcc, 0, v5, vcc
	v_lshl_add_u64 v[6:7], v[6:7], 0, v[154:155]
	v_mad_i64_i32 v[8:9], s[24:25], v8, s33, v[0:1]
	v_add_co_u32_e32 v6, vcc, s46, v6
	v_lshl_add_u64 v[8:9], v[8:9], 0, s[10:11]
	v_or_b32_e32 v10, s9, v182
	v_addc_co_u32_e32 v7, vcc, 0, v7, vcc
	v_lshl_add_u64 v[8:9], v[8:9], 0, v[154:155]
	v_mad_i64_i32 v[10:11], s[24:25], v10, s33, v[0:1]
	v_add_co_u32_e32 v8, vcc, s46, v8
	v_lshl_add_u64 v[10:11], v[10:11], 0, s[10:11]
	v_or_b32_e32 v12, s9, v183
	v_addc_co_u32_e32 v9, vcc, 0, v9, vcc
	v_lshl_add_u64 v[10:11], v[10:11], 0, v[154:155]
	v_mad_i64_i32 v[12:13], s[24:25], v12, s33, v[0:1]
	v_add_co_u32_e32 v10, vcc, s46, v10
	v_lshl_add_u64 v[12:13], v[12:13], 0, s[10:11]
	v_or_b32_e32 v14, s9, v184
	v_addc_co_u32_e32 v11, vcc, 0, v11, vcc
	v_lshl_add_u64 v[12:13], v[12:13], 0, v[154:155]
	v_mad_i64_i32 v[14:15], s[24:25], v14, s33, v[0:1]
	v_add_co_u32_e32 v12, vcc, s46, v12
	v_lshl_add_u64 v[14:15], v[14:15], 0, s[10:11]
	v_or_b32_e32 v16, s9, v185
	v_addc_co_u32_e32 v13, vcc, 0, v13, vcc
	v_lshl_add_u64 v[14:15], v[14:15], 0, v[154:155]
	v_mad_i64_i32 v[16:17], s[24:25], v16, s33, v[0:1]
	v_add_co_u32_e32 v14, vcc, s46, v14
	v_lshl_add_u64 v[16:17], v[16:17], 0, s[10:11]
	v_or_b32_e32 v18, s9, v186
	v_addc_co_u32_e32 v15, vcc, 0, v15, vcc
	v_lshl_add_u64 v[16:17], v[16:17], 0, v[154:155]
	v_mad_i64_i32 v[18:19], s[24:25], v18, s33, v[0:1]
	v_add_co_u32_e32 v16, vcc, s46, v16
	v_lshl_add_u64 v[18:19], v[18:19], 0, s[10:11]
	v_or_b32_e32 v20, s9, v188
	v_addc_co_u32_e32 v17, vcc, 0, v17, vcc
	v_lshl_add_u64 v[18:19], v[18:19], 0, v[154:155]
	v_mad_i64_i32 v[20:21], s[24:25], v20, s33, v[0:1]
	v_add_co_u32_e32 v18, vcc, s46, v18
	v_lshl_add_u64 v[20:21], v[20:21], 0, s[10:11]
	v_or_b32_e32 v22, s9, v189
	v_addc_co_u32_e32 v19, vcc, 0, v19, vcc
	v_lshl_add_u64 v[20:21], v[20:21], 0, v[154:155]
	v_mad_i64_i32 v[22:23], s[24:25], v22, s33, v[0:1]
	v_add_co_u32_e32 v20, vcc, s46, v20
	v_lshl_add_u64 v[22:23], v[22:23], 0, s[10:11]
	v_or_b32_e32 v24, s9, v190
	v_addc_co_u32_e32 v21, vcc, 0, v21, vcc
	v_lshl_add_u64 v[22:23], v[22:23], 0, v[154:155]
	v_mad_i64_i32 v[24:25], s[24:25], v24, s33, v[0:1]
	v_add_co_u32_e32 v22, vcc, s46, v22
	v_lshl_add_u64 v[24:25], v[24:25], 0, s[10:11]
	v_or_b32_e32 v26, s9, v191
	v_addc_co_u32_e32 v23, vcc, 0, v23, vcc
	v_lshl_add_u64 v[24:25], v[24:25], 0, v[154:155]
	v_mad_i64_i32 v[26:27], s[24:25], v26, s33, v[0:1]
	v_add_co_u32_e32 v24, vcc, s46, v24
	v_lshl_add_u64 v[26:27], v[26:27], 0, s[10:11]
	v_or_b32_e32 v28, s9, v192
	v_addc_co_u32_e32 v25, vcc, 0, v25, vcc
	v_lshl_add_u64 v[26:27], v[26:27], 0, v[154:155]
	v_mad_i64_i32 v[28:29], s[24:25], v28, s33, v[0:1]
	v_add_co_u32_e32 v26, vcc, s46, v26
	v_lshl_add_u64 v[28:29], v[28:29], 0, s[10:11]
	v_or_b32_e32 v30, s9, v193
	v_addc_co_u32_e32 v27, vcc, 0, v27, vcc
	v_lshl_add_u64 v[28:29], v[28:29], 0, v[154:155]
	v_mad_i64_i32 v[30:31], s[24:25], v30, s33, v[0:1]
	v_add_co_u32_e32 v28, vcc, s46, v28
	v_lshl_add_u64 v[30:31], v[30:31], 0, s[10:11]
	v_or_b32_e32 v32, s9, v194
	v_addc_co_u32_e32 v29, vcc, 0, v29, vcc
	v_lshl_add_u64 v[30:31], v[30:31], 0, v[154:155]
	v_mad_i64_i32 v[0:1], s[24:25], v32, s33, v[0:1]
	v_add_co_u32_e32 v30, vcc, s46, v30
	v_lshl_add_u64 v[0:1], v[0:1], 0, s[10:11]
	s_bfe_u32 s7, s6, 0x70004
	v_addc_co_u32_e32 v31, vcc, 0, v31, vcc
	v_lshl_add_u64 v[0:1], v[0:1], 0, v[154:155]
	s_lshl_b32 s8, s7, 15
	v_add_co_u32_e32 v0, vcc, s46, v0
	s_mov_b32 s9, s96
	s_nop 0
	v_addc_co_u32_e32 v1, vcc, 0, v1, vcc
	v_lshl_add_u64 v[170:171], v[96:97], 0, s[8:9]
	global_load_dwordx2 v[100:101], v[2:3], off
	global_load_dwordx2 v[106:107], v[4:5], off
	global_load_dwordx2 v[108:109], v[6:7], off
	global_load_dwordx2 v[116:117], v[8:9], off
	global_load_dwordx2 v[114:115], v[10:11], off
	global_load_dwordx2 v[124:125], v[12:13], off
	global_load_dwordx2 v[126:127], v[14:15], off
	global_load_dwordx2 v[134:135], v[16:17], off
	global_load_dwordx2 v[118:119], v[18:19], off
	global_load_dwordx2 v[132:133], v[20:21], off
	global_load_dwordx2 v[128:129], v[22:23], off
	global_load_dwordx2 v[142:143], v[24:25], off
	global_load_dwordx2 v[130:131], v[26:27], off
	global_load_dwordx2 v[144:145], v[28:29], off
	global_load_dwordx2 v[136:137], v[30:31], off
	global_load_dwordx2 v[146:147], v[0:1], off
	global_load_dwordx2 v[164:165], v[2:3], off offset:2048
	global_load_dwordx2 v[166:167], v[4:5], off offset:2048
	global_load_dwordx2 v[160:161], v[6:7], off offset:2048
	global_load_dwordx2 v[162:163], v[8:9], off offset:2048
	global_load_dwordx2 v[156:157], v[10:11], off offset:2048
	global_load_dwordx2 v[158:159], v[12:13], off offset:2048
	global_load_dwordx2 v[148:149], v[14:15], off offset:2048
	global_load_dwordx2 v[150:151], v[16:17], off offset:2048
	global_load_dwordx2 v[138:139], v[18:19], off offset:2048
	global_load_dwordx2 v[140:141], v[20:21], off offset:2048
	global_load_dwordx2 v[120:121], v[22:23], off offset:2048
	global_load_dwordx2 v[122:123], v[24:25], off offset:2048
	global_load_dwordx2 v[110:111], v[26:27], off offset:2048
	global_load_dwordx2 v[112:113], v[28:29], off offset:2048
	global_load_dwordx2 v[102:103], v[30:31], off offset:2048
	global_load_dwordx2 v[104:105], v[0:1], off offset:2048
	global_load_dwordx2 v[76:77], v[170:171], off
	global_load_dwordx2 v[78:79], v[170:171], off offset:32
	global_load_dwordx2 v[72:73], v[170:171], off offset:64
	global_load_dwordx2 v[74:75], v[170:171], off offset:96
	global_load_dwordx2 v[68:69], v[170:171], off offset:128
	global_load_dwordx2 v[70:71], v[170:171], off offset:160
	global_load_dwordx2 v[64:65], v[170:171], off offset:192
	global_load_dwordx2 v[66:67], v[170:171], off offset:224
	v_add_co_u32_e32 v82, vcc, s46, v170
	ds_read_b64_tr_b16 v[50:51], v195 offset:2304
	ds_read_b64_tr_b16 v[48:49], v195
	ds_read_b64_tr_b16 v[52:53], v195 offset:32
	ds_read_b64_tr_b16 v[54:55], v195 offset:2336
	ds_read_b64_tr_b16 v[56:57], v195 offset:64
	ds_read_b64_tr_b16 v[58:59], v195 offset:2368
	ds_read_b64_tr_b16 v[60:61], v195 offset:96
	ds_read_b64_tr_b16 v[62:63], v195 offset:2400
	ds_read_b64_tr_b16 v[32:33], v195 offset:4608
	ds_read_b64_tr_b16 v[34:35], v195 offset:6912
	ds_read_b64_tr_b16 v[36:37], v195 offset:4640
	ds_read_b64_tr_b16 v[38:39], v195 offset:6944
	ds_read_b64_tr_b16 v[40:41], v195 offset:4672
	ds_read_b64_tr_b16 v[42:43], v195 offset:6976
	ds_read_b64_tr_b16 v[44:45], v195 offset:4704
	ds_read_b64_tr_b16 v[46:47], v195 offset:7008
	ds_read_b64_tr_b16 v[16:17], v195 offset:9216
	ds_read_b64_tr_b16 v[18:19], v195 offset:11520
	ds_read_b64_tr_b16 v[20:21], v195 offset:9248
	ds_read_b64_tr_b16 v[22:23], v195 offset:11552
	ds_read_b64_tr_b16 v[24:25], v195 offset:9280
	ds_read_b64_tr_b16 v[26:27], v195 offset:11584
	ds_read_b64_tr_b16 v[28:29], v195 offset:9312
	ds_read_b64_tr_b16 v[30:31], v195 offset:11616
	ds_read_b64_tr_b16 v[0:1], v195 offset:13824
	ds_read_b64_tr_b16 v[2:3], v195 offset:16128
	ds_read_b64_tr_b16 v[4:5], v195 offset:13856
	ds_read_b64_tr_b16 v[6:7], v195 offset:16160
	ds_read_b64_tr_b16 v[8:9], v195 offset:13888
	ds_read_b64_tr_b16 v[10:11], v195 offset:16192
	ds_read_b64_tr_b16 v[12:13], v195 offset:13920
	ds_read_b64_tr_b16 v[14:15], v195 offset:16224
	v_addc_co_u32_e32 v83, vcc, 0, v171, vcc
	v_add_co_u32_e32 v174, vcc, s69, v170
	s_waitcnt vmcnt(6) lgkmcnt(14)
	v_mfma_f32_16x16x32_bf16 v[204:207], v[48:51], v[76:79], 0
	v_addc_co_u32_e32 v175, vcc, 0, v171, vcc
	global_load_dwordx2 v[92:93], v[174:175], off offset:-4096
	global_load_dwordx2 v[94:95], v[82:83], off offset:32
	global_load_dwordx2 v[88:89], v[82:83], off offset:64
	global_load_dwordx2 v[90:91], v[82:83], off offset:96
	global_load_dwordx2 v[84:85], v[82:83], off offset:128
	global_load_dwordx2 v[86:87], v[82:83], off offset:160
	global_load_dwordx2 v[80:81], v[82:83], off offset:192
	s_nop 0
	global_load_dwordx2 v[82:83], v[82:83], off offset:224
	v_mfma_f32_16x16x32_bf16 v[208:211], v[52:55], v[76:79], 0
	s_ashr_i32 s18, s6, 5
	s_and_b32 s6, s3, 0x3c0
	s_andn2_b32 s18, s18, 63
	v_mfma_f32_16x16x32_bf16 v[212:215], v[56:59], v[76:79], 0
	s_lshl_b32 s6, s6, 1
	v_lshl_or_b32 v172, s7, 1, v196
	s_mov_b32 s7, s96
	v_mfma_f32_16x16x32_bf16 v[76:79], v[60:63], v[76:79], 0
	v_lshl_add_u64 v[168:169], v[98:99], 0, s[6:7]
	v_or_b32_e32 v173, s18, v197
	s_movk_i32 s6, 0x101
	s_waitcnt vmcnt(12)
	v_mfma_f32_16x16x32_bf16 v[204:207], v[32:35], v[72:75], v[204:207]
	v_mad_u64_u32 v[172:173], s[6:7], v173, s6, v[172:173]
	v_ashrrev_i32_e32 v173, 31, v172
	v_mfma_f32_16x16x32_bf16 v[208:211], v[36:39], v[72:75], v[208:211]
	s_movk_i32 s6, 0x4000
	s_add_i32 s3, s3, s12
	s_cmpk_gt_i32 s13, 0xfff
	v_mfma_f32_16x16x32_bf16 v[212:215], v[40:43], v[72:75], v[212:215]
	v_mfma_f32_16x16x32_bf16 v[72:75], v[44:47], v[72:75], v[76:79]
	s_waitcnt vmcnt(10)
	v_mfma_f32_16x16x32_bf16 v[76:79], v[16:19], v[68:71], v[204:207]
	s_waitcnt lgkmcnt(12)
	v_mfma_f32_16x16x32_bf16 v[204:207], v[20:23], v[68:71], v[208:211]
	s_waitcnt lgkmcnt(10)
	v_mfma_f32_16x16x32_bf16 v[208:211], v[24:27], v[68:71], v[212:215]
	s_waitcnt lgkmcnt(8)
	v_mfma_f32_16x16x32_bf16 v[212:215], v[28:31], v[68:71], v[72:75]
	s_waitcnt vmcnt(8) lgkmcnt(6)
	v_mfma_f32_16x16x32_bf16 v[76:79], v[0:3], v[64:67], v[76:79]
	s_waitcnt lgkmcnt(4)
	v_mfma_f32_16x16x32_bf16 v[72:75], v[4:7], v[64:67], v[204:207]
	s_waitcnt lgkmcnt(2)
	v_mfma_f32_16x16x32_bf16 v[68:71], v[8:11], v[64:67], v[208:211]
	s_nop 0
	v_lshlrev_b64 v[204:205], 11, v[172:173]
	v_lshl_add_u64 v[204:205], v[168:169], 0, v[204:205]
	s_nop 0
	v_cvt_pk_bf16_f32 v76, v76, v77
	s_waitcnt lgkmcnt(0)
	v_mfma_f32_16x16x32_bf16 v[64:67], v[12:15], v[64:67], v[212:215]
	v_cvt_pk_bf16_f32 v77, v78, v79
	v_cvt_pk_bf16_f32 v72, v72, v73
	v_cvt_pk_bf16_f32 v73, v74, v75
	v_cvt_pk_bf16_f32 v68, v68, v69
	v_cvt_pk_bf16_f32 v69, v70, v71
	s_nop 2
	v_cvt_pk_bf16_f32 v64, v64, v65
	v_cvt_pk_bf16_f32 v65, v66, v67
	ds_write_b64 v216, v[76:77]
	ds_write_b64 v216, v[72:73] offset:32
	ds_write_b64 v216, v[68:69] offset:64
	ds_write_b64 v216, v[64:65] offset:96
	v_readfirstlane_b32 s98, v204
	v_readfirstlane_b32 s99, v205
	ds_read_b64 v[220:221], v217
	ds_read_b64 v[222:223], v217 offset:576
	ds_read_b64 v[224:225], v217 offset:1152
	ds_read_b64 v[226:227], v217 offset:1728
	s_waitcnt lgkmcnt(3)
	global_store_dwordx2 v218, v[220:221], s[98:99]
	s_waitcnt lgkmcnt(2)
	global_store_dwordx2 v219, v[222:223], s[98:99]
	s_waitcnt lgkmcnt(1)
	global_store_dwordx2 v228, v[224:225], s[98:99]
	s_waitcnt lgkmcnt(0)
	global_store_dwordx2 v229, v[226:227], s[98:99]
	s_waitcnt vmcnt(10)
	v_mfma_f32_16x16x32_bf16 v[204:207], v[48:51], v[92:95], 0
	global_load_dwordx2 v[76:77], v[174:175], off
	global_load_dwordx2 v[78:79], v[174:175], off offset:32
	global_load_dwordx2 v[72:73], v[174:175], off offset:64
	global_load_dwordx2 v[74:75], v[174:175], off offset:96
	global_load_dwordx2 v[68:69], v[174:175], off offset:128
	global_load_dwordx2 v[70:71], v[174:175], off offset:160
	global_load_dwordx2 v[64:65], v[174:175], off offset:192
	global_load_dwordx2 v[66:67], v[174:175], off offset:224
	v_mfma_f32_16x16x32_bf16 v[208:211], v[52:55], v[92:95], 0
	v_mfma_f32_16x16x32_bf16 v[212:215], v[56:59], v[92:95], 0
	v_mfma_f32_16x16x32_bf16 v[92:95], v[60:63], v[92:95], 0
	s_waitcnt vmcnt(16)
	v_mfma_f32_16x16x32_bf16 v[204:207], v[32:35], v[88:91], v[204:207]
	v_mfma_f32_16x16x32_bf16 v[208:211], v[36:39], v[88:91], v[208:211]
	v_mfma_f32_16x16x32_bf16 v[212:215], v[40:43], v[88:91], v[212:215]
	v_mfma_f32_16x16x32_bf16 v[88:91], v[44:47], v[88:91], v[92:95]
	s_waitcnt vmcnt(14)
	v_mfma_f32_16x16x32_bf16 v[92:95], v[16:19], v[84:87], v[204:207]
	v_mfma_f32_16x16x32_bf16 v[204:207], v[20:23], v[84:87], v[208:211]
	v_mfma_f32_16x16x32_bf16 v[208:211], v[24:27], v[84:87], v[212:215]
	v_mfma_f32_16x16x32_bf16 v[84:87], v[28:31], v[84:87], v[88:91]
	s_waitcnt vmcnt(12)
	v_mfma_f32_16x16x32_bf16 v[88:91], v[0:3], v[80:83], v[92:95]
	v_mfma_f32_16x16x32_bf16 v[92:95], v[4:7], v[80:83], v[204:207]
	v_mfma_f32_16x16x32_bf16 v[204:207], v[8:11], v[80:83], v[208:211]
	v_mfma_f32_16x16x32_bf16 v[80:83], v[12:15], v[80:83], v[84:87]
	s_nop 2
	v_add_u32_e32 v84, 0x808, v172
	v_ashrrev_i32_e32 v85, 31, v84
	v_lshlrev_b64 v[84:85], 11, v[84:85]
	v_lshl_add_u64 v[84:85], v[168:169], 0, v[84:85]
	v_cvt_pk_bf16_f32 v86, v88, v89
	v_cvt_pk_bf16_f32 v87, v90, v91
	v_cvt_pk_bf16_f32 v80, v80, v81
	v_cvt_pk_bf16_f32 v81, v82, v83
	v_add_co_u32_e32 v82, vcc, s64, v170
	ds_write_b64 v216, v[86:87]
	v_cvt_pk_bf16_f32 v86, v92, v93
	v_cvt_pk_bf16_f32 v87, v94, v95
	v_addc_co_u32_e32 v83, vcc, 0, v171, vcc
	ds_write_b64 v216, v[86:87] offset:32
	v_cvt_pk_bf16_f32 v86, v204, v205
	v_cvt_pk_bf16_f32 v87, v206, v207
	v_add_co_u32_e32 v174, vcc, s6, v170
	ds_write_b64 v216, v[86:87] offset:64
	ds_write_b64 v216, v[80:81] offset:96
	v_readfirstlane_b32 s98, v84
	v_readfirstlane_b32 s99, v85
	ds_read_b64 v[220:221], v217
	ds_read_b64 v[222:223], v217 offset:576
	ds_read_b64 v[224:225], v217 offset:1152
	ds_read_b64 v[226:227], v217 offset:1728
	s_waitcnt lgkmcnt(3)
	global_store_dwordx2 v218, v[220:221], s[98:99]
	s_waitcnt lgkmcnt(2)
	global_store_dwordx2 v219, v[222:223], s[98:99]
	s_waitcnt lgkmcnt(1)
	global_store_dwordx2 v228, v[224:225], s[98:99]
	s_waitcnt lgkmcnt(0)
	global_store_dwordx2 v229, v[226:227], s[98:99]
	v_addc_co_u32_e32 v175, vcc, 0, v171, vcc
	global_load_dwordx2 v[92:93], v[174:175], off offset:-4096
	global_load_dwordx2 v[94:95], v[82:83], off offset:32
	global_load_dwordx2 v[88:89], v[82:83], off offset:64
	global_load_dwordx2 v[90:91], v[82:83], off offset:96
	global_load_dwordx2 v[84:85], v[82:83], off offset:128
	global_load_dwordx2 v[86:87], v[82:83], off offset:160
	global_load_dwordx2 v[80:81], v[82:83], off offset:192
	s_nop 0
	global_load_dwordx2 v[82:83], v[82:83], off offset:224
	s_waitcnt vmcnt(18)
	v_mfma_f32_16x16x32_bf16 v[204:207], v[48:51], v[76:79], 0
	s_movk_i32 s6, 0x6000
	v_mfma_f32_16x16x32_bf16 v[208:211], v[52:55], v[76:79], 0
	v_mfma_f32_16x16x32_bf16 v[212:215], v[56:59], v[76:79], 0
	v_mfma_f32_16x16x32_bf16 v[76:79], v[60:63], v[76:79], 0
	s_waitcnt vmcnt(16)
	v_mfma_f32_16x16x32_bf16 v[204:207], v[32:35], v[72:75], v[204:207]
	v_mfma_f32_16x16x32_bf16 v[208:211], v[36:39], v[72:75], v[208:211]
	v_mfma_f32_16x16x32_bf16 v[212:215], v[40:43], v[72:75], v[212:215]
	v_mfma_f32_16x16x32_bf16 v[72:75], v[44:47], v[72:75], v[76:79]
	s_waitcnt vmcnt(14)
	v_mfma_f32_16x16x32_bf16 v[76:79], v[16:19], v[68:71], v[204:207]
	v_mfma_f32_16x16x32_bf16 v[204:207], v[20:23], v[68:71], v[208:211]
	v_mfma_f32_16x16x32_bf16 v[208:211], v[24:27], v[68:71], v[212:215]
	v_mfma_f32_16x16x32_bf16 v[68:71], v[28:31], v[68:71], v[72:75]
	s_waitcnt vmcnt(12)
	v_mfma_f32_16x16x32_bf16 v[72:75], v[0:3], v[64:67], v[76:79]
	v_mfma_f32_16x16x32_bf16 v[76:79], v[4:7], v[64:67], v[204:207]
	v_mfma_f32_16x16x32_bf16 v[204:207], v[8:11], v[64:67], v[208:211]
	v_mfma_f32_16x16x32_bf16 v[64:67], v[12:15], v[64:67], v[68:71]
	s_nop 2
	v_add_u32_e32 v68, 0x1010, v172
	v_ashrrev_i32_e32 v69, 31, v68
	v_lshlrev_b64 v[68:69], 11, v[68:69]
	v_lshl_add_u64 v[68:69], v[168:169], 0, v[68:69]
	v_cvt_pk_bf16_f32 v70, v72, v73
	v_cvt_pk_bf16_f32 v71, v74, v75
	ds_write_b64 v216, v[70:71]
	v_cvt_pk_bf16_f32 v70, v76, v77
	v_cvt_pk_bf16_f32 v71, v78, v79
	ds_write_b64 v216, v[70:71] offset:32
	v_cvt_pk_bf16_f32 v70, v204, v205
	v_cvt_pk_bf16_f32 v71, v206, v207
	v_cvt_pk_bf16_f32 v64, v64, v65
	v_cvt_pk_bf16_f32 v65, v66, v67
	s_waitcnt vmcnt(6)
	v_mfma_f32_16x16x32_bf16 v[204:207], v[48:51], v[92:95], 0
	ds_write_b64 v216, v[70:71] offset:64
	ds_write_b64 v216, v[64:65] offset:96
	v_readfirstlane_b32 s98, v68
	v_readfirstlane_b32 s99, v69
	ds_read_b64 v[220:221], v217
	ds_read_b64 v[222:223], v217 offset:576
	ds_read_b64 v[224:225], v217 offset:1152
	ds_read_b64 v[226:227], v217 offset:1728
	s_waitcnt lgkmcnt(3)
	global_store_dwordx2 v218, v[220:221], s[98:99]
	s_waitcnt lgkmcnt(2)
	global_store_dwordx2 v219, v[222:223], s[98:99]
	s_waitcnt lgkmcnt(1)
	global_store_dwordx2 v228, v[224:225], s[98:99]
	s_waitcnt lgkmcnt(0)
	global_store_dwordx2 v229, v[226:227], s[98:99]
	global_load_dwordx2 v[76:77], v[174:175], off
	global_load_dwordx2 v[78:79], v[174:175], off offset:32
	global_load_dwordx2 v[72:73], v[174:175], off offset:64
	global_load_dwordx2 v[74:75], v[174:175], off offset:96
	s_nop 0
	global_load_dwordx2 v[68:69], v[174:175], off offset:128
	global_load_dwordx2 v[70:71], v[174:175], off offset:160
	global_load_dwordx2 v[64:65], v[174:175], off offset:192
	global_load_dwordx2 v[66:67], v[174:175], off offset:224
	v_mfma_f32_16x16x32_bf16 v[208:211], v[52:55], v[92:95], 0
	v_mfma_f32_16x16x32_bf16 v[212:215], v[56:59], v[92:95], 0
	v_mfma_f32_16x16x32_bf16 v[92:95], v[60:63], v[92:95], 0
	s_waitcnt vmcnt(16)
	v_mfma_f32_16x16x32_bf16 v[204:207], v[32:35], v[88:91], v[204:207]
	v_mfma_f32_16x16x32_bf16 v[208:211], v[36:39], v[88:91], v[208:211]
	v_mfma_f32_16x16x32_bf16 v[212:215], v[40:43], v[88:91], v[212:215]
	v_mfma_f32_16x16x32_bf16 v[88:91], v[44:47], v[88:91], v[92:95]
	s_waitcnt vmcnt(14)
	v_mfma_f32_16x16x32_bf16 v[92:95], v[16:19], v[84:87], v[204:207]
	v_mfma_f32_16x16x32_bf16 v[204:207], v[20:23], v[84:87], v[208:211]
	v_mfma_f32_16x16x32_bf16 v[208:211], v[24:27], v[84:87], v[212:215]
	v_mfma_f32_16x16x32_bf16 v[84:87], v[28:31], v[84:87], v[88:91]
	s_waitcnt vmcnt(12)
	v_mfma_f32_16x16x32_bf16 v[88:91], v[0:3], v[80:83], v[92:95]
	v_mfma_f32_16x16x32_bf16 v[92:95], v[4:7], v[80:83], v[204:207]
	v_mfma_f32_16x16x32_bf16 v[204:207], v[8:11], v[80:83], v[208:211]
	v_mfma_f32_16x16x32_bf16 v[80:83], v[12:15], v[80:83], v[84:87]
	s_nop 2
	v_add_u32_e32 v84, 0x1818, v172
	v_ashrrev_i32_e32 v85, 31, v84
	v_lshlrev_b64 v[84:85], 11, v[84:85]
	v_lshl_add_u64 v[84:85], v[168:169], 0, v[84:85]
	v_cvt_pk_bf16_f32 v86, v88, v89
	v_cvt_pk_bf16_f32 v87, v90, v91
	v_cvt_pk_bf16_f32 v80, v80, v81
	v_cvt_pk_bf16_f32 v81, v82, v83
	v_add_co_u32_e32 v82, vcc, s35, v170
	ds_write_b64 v216, v[86:87]
	v_cvt_pk_bf16_f32 v86, v92, v93
	v_cvt_pk_bf16_f32 v87, v94, v95
	v_addc_co_u32_e32 v83, vcc, 0, v171, vcc
	ds_write_b64 v216, v[86:87] offset:32
	v_cvt_pk_bf16_f32 v86, v204, v205
	v_cvt_pk_bf16_f32 v87, v206, v207
	v_add_co_u32_e32 v174, vcc, s6, v170
	ds_write_b64 v216, v[86:87] offset:64
	ds_write_b64 v216, v[80:81] offset:96
	v_readfirstlane_b32 s98, v84
	v_readfirstlane_b32 s99, v85
	ds_read_b64 v[220:221], v217
	ds_read_b64 v[222:223], v217 offset:576
	ds_read_b64 v[224:225], v217 offset:1152
	ds_read_b64 v[226:227], v217 offset:1728
	s_waitcnt lgkmcnt(3)
	global_store_dwordx2 v218, v[220:221], s[98:99]
	s_waitcnt lgkmcnt(2)
	global_store_dwordx2 v219, v[222:223], s[98:99]
	s_waitcnt lgkmcnt(1)
	global_store_dwordx2 v228, v[224:225], s[98:99]
	s_waitcnt lgkmcnt(0)
	global_store_dwordx2 v229, v[226:227], s[98:99]
	v_addc_co_u32_e32 v175, vcc, 0, v171, vcc
	global_load_dwordx2 v[92:93], v[174:175], off offset:-4096
	global_load_dwordx2 v[94:95], v[82:83], off offset:32
	global_load_dwordx2 v[88:89], v[82:83], off offset:64
	global_load_dwordx2 v[90:91], v[82:83], off offset:96
	global_load_dwordx2 v[84:85], v[82:83], off offset:128
	global_load_dwordx2 v[86:87], v[82:83], off offset:160
	global_load_dwordx2 v[80:81], v[82:83], off offset:192
	s_nop 0
	global_load_dwordx2 v[82:83], v[82:83], off offset:224
	s_waitcnt vmcnt(18)
	v_mfma_f32_16x16x32_bf16 v[204:207], v[48:51], v[76:79], 0
	s_movk_i32 s6, 0x7000
	v_mfma_f32_16x16x32_bf16 v[208:211], v[52:55], v[76:79], 0
	v_mfma_f32_16x16x32_bf16 v[212:215], v[56:59], v[76:79], 0
	v_mfma_f32_16x16x32_bf16 v[76:79], v[60:63], v[76:79], 0
	s_waitcnt vmcnt(16)
	v_mfma_f32_16x16x32_bf16 v[204:207], v[32:35], v[72:75], v[204:207]
	v_mfma_f32_16x16x32_bf16 v[208:211], v[36:39], v[72:75], v[208:211]
	v_mfma_f32_16x16x32_bf16 v[212:215], v[40:43], v[72:75], v[212:215]
	v_mfma_f32_16x16x32_bf16 v[72:75], v[44:47], v[72:75], v[76:79]
	s_waitcnt vmcnt(14)
	v_mfma_f32_16x16x32_bf16 v[76:79], v[16:19], v[68:71], v[204:207]
	v_mfma_f32_16x16x32_bf16 v[204:207], v[20:23], v[68:71], v[208:211]
	v_mfma_f32_16x16x32_bf16 v[208:211], v[24:27], v[68:71], v[212:215]
	v_mfma_f32_16x16x32_bf16 v[68:71], v[28:31], v[68:71], v[72:75]
	s_waitcnt vmcnt(12)
	v_mfma_f32_16x16x32_bf16 v[72:75], v[0:3], v[64:67], v[76:79]
	v_mfma_f32_16x16x32_bf16 v[76:79], v[4:7], v[64:67], v[204:207]
	v_mfma_f32_16x16x32_bf16 v[204:207], v[8:11], v[64:67], v[208:211]
	v_mfma_f32_16x16x32_bf16 v[64:67], v[12:15], v[64:67], v[68:71]
	s_nop 2
	v_add_u32_e32 v68, 0x2020, v172
	v_ashrrev_i32_e32 v69, 31, v68
	v_lshlrev_b64 v[68:69], 11, v[68:69]
	v_lshl_add_u64 v[68:69], v[168:169], 0, v[68:69]
	v_cvt_pk_bf16_f32 v70, v72, v73
	v_cvt_pk_bf16_f32 v71, v74, v75
	ds_write_b64 v216, v[70:71]
	v_cvt_pk_bf16_f32 v70, v76, v77
	v_cvt_pk_bf16_f32 v71, v78, v79
	ds_write_b64 v216, v[70:71] offset:32
	v_cvt_pk_bf16_f32 v70, v204, v205
	v_cvt_pk_bf16_f32 v71, v206, v207
	s_waitcnt vmcnt(6)
	v_mfma_f32_16x16x32_bf16 v[204:207], v[48:51], v[92:95], 0
	v_cvt_pk_bf16_f32 v64, v64, v65
	v_cvt_pk_bf16_f32 v65, v66, v67
	ds_write_b64 v216, v[70:71] offset:64
	v_mfma_f32_16x16x32_bf16 v[208:211], v[52:55], v[92:95], 0
	ds_write_b64 v216, v[64:65] offset:96
	v_readfirstlane_b32 s98, v68
	v_readfirstlane_b32 s99, v69
	ds_read_b64 v[220:221], v217
	ds_read_b64 v[222:223], v217 offset:576
	ds_read_b64 v[224:225], v217 offset:1152
	ds_read_b64 v[226:227], v217 offset:1728
	s_waitcnt lgkmcnt(3)
	global_store_dwordx2 v218, v[220:221], s[98:99]
	s_waitcnt lgkmcnt(2)
	global_store_dwordx2 v219, v[222:223], s[98:99]
	s_waitcnt lgkmcnt(1)
	global_store_dwordx2 v228, v[224:225], s[98:99]
	s_waitcnt lgkmcnt(0)
	global_store_dwordx2 v229, v[226:227], s[98:99]
	global_load_dwordx2 v[76:77], v[174:175], off
	global_load_dwordx2 v[78:79], v[174:175], off offset:32
	global_load_dwordx2 v[72:73], v[174:175], off offset:64
	global_load_dwordx2 v[74:75], v[174:175], off offset:96
	s_nop 0
	global_load_dwordx2 v[68:69], v[174:175], off offset:128
	global_load_dwordx2 v[70:71], v[174:175], off offset:160
	global_load_dwordx2 v[64:65], v[174:175], off offset:192
	global_load_dwordx2 v[66:67], v[174:175], off offset:224
	v_mfma_f32_16x16x32_bf16 v[212:215], v[56:59], v[92:95], 0
	v_mfma_f32_16x16x32_bf16 v[92:95], v[60:63], v[92:95], 0
	s_waitcnt vmcnt(16)
	v_mfma_f32_16x16x32_bf16 v[204:207], v[32:35], v[88:91], v[204:207]
	v_mfma_f32_16x16x32_bf16 v[208:211], v[36:39], v[88:91], v[208:211]
	v_mfma_f32_16x16x32_bf16 v[212:215], v[40:43], v[88:91], v[212:215]
	v_mfma_f32_16x16x32_bf16 v[88:91], v[44:47], v[88:91], v[92:95]
	s_waitcnt vmcnt(14)
	v_mfma_f32_16x16x32_bf16 v[92:95], v[16:19], v[84:87], v[204:207]
	v_mfma_f32_16x16x32_bf16 v[204:207], v[20:23], v[84:87], v[208:211]
	v_mfma_f32_16x16x32_bf16 v[208:211], v[24:27], v[84:87], v[212:215]
	v_mfma_f32_16x16x32_bf16 v[84:87], v[28:31], v[84:87], v[88:91]
	s_waitcnt vmcnt(12)
	v_mfma_f32_16x16x32_bf16 v[88:91], v[0:3], v[80:83], v[92:95]
	v_mfma_f32_16x16x32_bf16 v[92:95], v[4:7], v[80:83], v[204:207]
	v_mfma_f32_16x16x32_bf16 v[204:207], v[8:11], v[80:83], v[208:211]
	v_mfma_f32_16x16x32_bf16 v[80:83], v[12:15], v[80:83], v[84:87]
	s_nop 2
	v_add_u32_e32 v84, 0x2828, v172
	v_ashrrev_i32_e32 v85, 31, v84
	v_lshlrev_b64 v[84:85], 11, v[84:85]
	v_lshl_add_u64 v[84:85], v[168:169], 0, v[84:85]
	v_cvt_pk_bf16_f32 v86, v88, v89
	v_cvt_pk_bf16_f32 v87, v90, v91
	ds_write_b64 v216, v[86:87]
	v_cvt_pk_bf16_f32 v86, v92, v93
	v_cvt_pk_bf16_f32 v87, v94, v95
	ds_write_b64 v216, v[86:87] offset:32
	v_cvt_pk_bf16_f32 v86, v204, v205
	v_cvt_pk_bf16_f32 v87, v206, v207
	v_cvt_pk_bf16_f32 v80, v80, v81
	v_cvt_pk_bf16_f32 v81, v82, v83
	v_add_co_u32_e32 v82, vcc, s6, v170
	ds_write_b64 v216, v[86:87] offset:64
	ds_write_b64 v216, v[80:81] offset:96
	v_readfirstlane_b32 s98, v84
	v_readfirstlane_b32 s99, v85
	ds_read_b64 v[220:221], v217
	ds_read_b64 v[222:223], v217 offset:576
	ds_read_b64 v[224:225], v217 offset:1152
	ds_read_b64 v[226:227], v217 offset:1728
	s_waitcnt lgkmcnt(3)
	global_store_dwordx2 v218, v[220:221], s[98:99]
	s_waitcnt lgkmcnt(2)
	global_store_dwordx2 v219, v[222:223], s[98:99]
	s_waitcnt lgkmcnt(1)
	global_store_dwordx2 v228, v[224:225], s[98:99]
	s_waitcnt lgkmcnt(0)
	global_store_dwordx2 v229, v[226:227], s[98:99]
	v_addc_co_u32_e32 v83, vcc, 0, v171, vcc
	global_load_dwordx2 v[92:93], v[82:83], off
	global_load_dwordx2 v[94:95], v[82:83], off offset:32
	global_load_dwordx2 v[88:89], v[82:83], off offset:64
	global_load_dwordx2 v[90:91], v[82:83], off offset:96
	global_load_dwordx2 v[84:85], v[82:83], off offset:128
	global_load_dwordx2 v[86:87], v[82:83], off offset:160
	global_load_dwordx2 v[80:81], v[82:83], off offset:192
	s_nop 0
	global_load_dwordx2 v[82:83], v[82:83], off offset:224
	s_waitcnt vmcnt(18)
	v_mfma_f32_16x16x32_bf16 v[204:207], v[48:51], v[76:79], 0
	s_mov_b32 s6, s13
	s_waitcnt vmcnt(6)
	v_mfma_f32_16x16x32_bf16 v[48:51], v[48:51], v[92:95], 0
	v_mfma_f32_16x16x32_bf16 v[208:211], v[52:55], v[76:79], 0
	v_mfma_f32_16x16x32_bf16 v[52:55], v[52:55], v[92:95], 0
	v_mfma_f32_16x16x32_bf16 v[212:215], v[56:59], v[76:79], 0
	v_mfma_f32_16x16x32_bf16 v[76:79], v[60:63], v[76:79], 0
	v_mfma_f32_16x16x32_bf16 v[56:59], v[56:59], v[92:95], 0
	v_mfma_f32_16x16x32_bf16 v[60:63], v[60:63], v[92:95], 0
	v_mfma_f32_16x16x32_bf16 v[204:207], v[32:35], v[72:75], v[204:207]
	s_waitcnt vmcnt(4)
	v_mfma_f32_16x16x32_bf16 v[32:35], v[32:35], v[88:91], v[48:51]
	v_mfma_f32_16x16x32_bf16 v[208:211], v[36:39], v[72:75], v[208:211]
	v_mfma_f32_16x16x32_bf16 v[36:39], v[36:39], v[88:91], v[52:55]
	v_mfma_f32_16x16x32_bf16 v[212:215], v[40:43], v[72:75], v[212:215]
	v_mfma_f32_16x16x32_bf16 v[72:75], v[44:47], v[72:75], v[76:79]
	v_mfma_f32_16x16x32_bf16 v[40:43], v[40:43], v[88:91], v[56:59]
	v_mfma_f32_16x16x32_bf16 v[44:47], v[44:47], v[88:91], v[60:63]
	v_mfma_f32_16x16x32_bf16 v[76:79], v[16:19], v[68:71], v[204:207]
	s_waitcnt vmcnt(2)
	v_mfma_f32_16x16x32_bf16 v[16:19], v[16:19], v[84:87], v[32:35]
	v_mfma_f32_16x16x32_bf16 v[204:207], v[20:23], v[68:71], v[208:211]
	v_mfma_f32_16x16x32_bf16 v[20:23], v[20:23], v[84:87], v[36:39]
	v_mfma_f32_16x16x32_bf16 v[208:211], v[24:27], v[68:71], v[212:215]
	v_mfma_f32_16x16x32_bf16 v[68:71], v[28:31], v[68:71], v[72:75]
	v_mfma_f32_16x16x32_bf16 v[24:27], v[24:27], v[84:87], v[40:43]
	v_mfma_f32_16x16x32_bf16 v[28:31], v[28:31], v[84:87], v[44:47]
	v_mfma_f32_16x16x32_bf16 v[72:75], v[0:3], v[64:67], v[76:79]
	s_waitcnt vmcnt(0)
	v_mfma_f32_16x16x32_bf16 v[0:3], v[0:3], v[80:83], v[16:19]
	v_mfma_f32_16x16x32_bf16 v[76:79], v[4:7], v[64:67], v[204:207]
	s_nop 1
	v_add_u32_e32 v16, 0x3838, v172
	v_ashrrev_i32_e32 v17, 31, v16
	v_lshlrev_b64 v[16:17], 11, v[16:17]
	v_mfma_f32_16x16x32_bf16 v[4:7], v[4:7], v[80:83], v[20:23]
	v_lshl_add_u64 v[16:17], v[168:169], 0, v[16:17]
	v_cvt_pk_bf16_f32 v0, v0, v1
	v_cvt_pk_bf16_f32 v1, v2, v3
	v_mfma_f32_16x16x32_bf16 v[204:207], v[8:11], v[64:67], v[208:211]
	ds_write_b64 v216, v[0:1]
	s_nop 2
	v_cvt_pk_bf16_f32 v0, v4, v5
	v_cvt_pk_bf16_f32 v1, v6, v7
	v_mfma_f32_16x16x32_bf16 v[64:67], v[12:15], v[64:67], v[68:71]
	ds_write_b64 v216, v[0:1] offset:32
	s_nop 1
	v_add_u32_e32 v68, 0x3030, v172
	v_mfma_f32_16x16x32_bf16 v[8:11], v[8:11], v[80:83], v[24:27]
	v_ashrrev_i32_e32 v69, 31, v68
	v_lshlrev_b64 v[68:69], 11, v[68:69]
	v_lshl_add_u64 v[68:69], v[168:169], 0, v[68:69]
	v_mfma_f32_16x16x32_bf16 v[12:15], v[12:15], v[80:83], v[28:31]
	v_cvt_pk_bf16_f32 v70, v72, v73
	v_cvt_pk_bf16_f32 v71, v74, v75
	ds_write_b64 v216, v[70:71] offset:2304
	v_cvt_pk_bf16_f32 v70, v76, v77
	v_cvt_pk_bf16_f32 v71, v78, v79
	v_cvt_pk_bf16_f32 v0, v8, v9
	v_cvt_pk_bf16_f32 v1, v10, v11
	ds_write_b64 v216, v[70:71] offset:2336
	v_cvt_pk_bf16_f32 v70, v204, v205
	v_cvt_pk_bf16_f32 v71, v206, v207
	v_cvt_pk_bf16_f32 v64, v64, v65
	v_cvt_pk_bf16_f32 v65, v66, v67
	ds_write_b64 v216, v[0:1] offset:64
	v_cvt_pk_bf16_f32 v0, v12, v13
	v_cvt_pk_bf16_f32 v1, v14, v15
	ds_write_b64 v216, v[70:71] offset:2368
	ds_write_b64 v216, v[64:65] offset:2400
	v_readfirstlane_b32 s100, v68
	v_readfirstlane_b32 s101, v69
	ds_read_b64 v[230:231], v217 offset:2304
	ds_read_b64 v[232:233], v217 offset:2880
	ds_read_b64 v[234:235], v217 offset:3456
	ds_read_b64 v[236:237], v217 offset:4032
	s_waitcnt lgkmcnt(3)
	global_store_dwordx2 v218, v[230:231], s[100:101]
	s_waitcnt lgkmcnt(2)
	global_store_dwordx2 v219, v[232:233], s[100:101]
	s_waitcnt lgkmcnt(1)
	global_store_dwordx2 v228, v[234:235], s[100:101]
	s_waitcnt lgkmcnt(0)
	global_store_dwordx2 v229, v[236:237], s[100:101]
	ds_write_b64 v216, v[0:1] offset:96
	v_readfirstlane_b32 s98, v16
	v_readfirstlane_b32 s99, v17
	ds_read_b64 v[220:221], v217
	ds_read_b64 v[222:223], v217 offset:576
	ds_read_b64 v[224:225], v217 offset:1152
	ds_read_b64 v[226:227], v217 offset:1728
	s_waitcnt lgkmcnt(3)
	global_store_dwordx2 v218, v[220:221], s[98:99]
	s_waitcnt lgkmcnt(2)
	global_store_dwordx2 v219, v[222:223], s[98:99]
	s_waitcnt lgkmcnt(1)
	global_store_dwordx2 v228, v[224:225], s[98:99]
	s_waitcnt lgkmcnt(0)
	global_store_dwordx2 v229, v[226:227], s[98:99]
	s_cbranch_scc0 .LBB0_129

.LBB0_134:
	s_bfe_u32 s10, s9, 0x50004
	s_ashr_i32 s11, s9, 9
	s_lshl_b32 s4, s11, 11
	s_lshl_b32 s5, s10, 2
	s_or_b32 s13, s4, s5
	v_or_b32_e32 v46, s13, v96
	v_mov_b64_e32 v[44:45], s[92:93]
	s_and_b32 s6, s2, 0x3c0
	v_mad_i64_i32 v[0:1], s[4:5], v46, s33, v[44:45]
	s_lshl_b32 s4, s6, 1
	s_mov_b32 s5, s96
	v_lshl_add_u64 v[0:1], v[0:1], 0, s[4:5]
	v_or_b32_e32 v47, s13, v97
	v_lshl_add_u64 v[0:1], v[0:1], 0, v[154:155]
	v_mad_i64_i32 v[2:3], s[6:7], v47, s33, v[44:45]
	v_add_co_u32_e32 v0, vcc, s46, v0
	v_lshl_add_u64 v[2:3], v[2:3], 0, s[4:5]
	v_or_b32_e32 v50, s13, v98
	v_addc_co_u32_e32 v1, vcc, 0, v1, vcc
	v_lshl_add_u64 v[2:3], v[2:3], 0, v[154:155]
	v_mad_i64_i32 v[4:5], s[6:7], v50, s33, v[44:45]
	v_add_co_u32_e32 v2, vcc, s46, v2
	v_lshl_add_u64 v[4:5], v[4:5], 0, s[4:5]
	s_nop 0
	v_addc_co_u32_e32 v3, vcc, 0, v3, vcc
	v_lshl_add_u64 v[4:5], v[4:5], 0, v[154:155]
	v_add_co_u32_e32 v6, vcc, s46, v4
	v_or_b32_e32 v51, s13, v99
	s_nop 0
	v_addc_co_u32_e32 v7, vcc, 0, v5, vcc
	v_mad_i64_i32 v[4:5], s[6:7], v51, s33, v[44:45]
	v_lshl_add_u64 v[4:5], v[4:5], 0, s[4:5]
	v_lshl_add_u64 v[4:5], v[4:5], 0, v[154:155]
	v_add_co_u32_e32 v8, vcc, s46, v4
	global_load_dwordx2 v[56:57], v[0:1], off
	global_load_dwordx2 v[58:59], v[2:3], off
	global_load_dwordx2 v[60:61], v[6:7], off
	v_addc_co_u32_e32 v9, vcc, 0, v5, vcc
	global_load_dwordx2 v[62:63], v[8:9], off
	s_nop 0
	global_load_dwordx2 v[0:1], v[0:1], off offset:2048
	s_nop 0
	global_load_dwordx2 v[4:5], v[2:3], off offset:2048
	s_nop 0
	global_load_dwordx2 v[6:7], v[6:7], off offset:2048
	s_nop 0
	global_load_dwordx2 v[8:9], v[8:9], off offset:2048
	v_or_b32_e32 v2, 1, v46
	v_mad_i64_i32 v[2:3], s[6:7], v2, s33, v[44:45]
	v_lshl_add_u64 v[2:3], v[2:3], 0, s[4:5]
	v_or_b32_e32 v10, 1, v47
	v_lshl_add_u64 v[2:3], v[2:3], 0, v[154:155]
	v_mad_i64_i32 v[10:11], s[6:7], v10, s33, v[44:45]
	v_add_co_u32_e32 v12, vcc, s46, v2
	v_lshl_add_u64 v[10:11], v[10:11], 0, s[4:5]
	v_or_b32_e32 v14, 1, v50
	v_addc_co_u32_e32 v13, vcc, 0, v3, vcc
	v_lshl_add_u64 v[10:11], v[10:11], 0, v[154:155]
	v_mad_i64_i32 v[14:15], s[6:7], v14, s33, v[44:45]
	v_add_co_u32_e32 v16, vcc, s46, v10
	v_lshl_add_u64 v[14:15], v[14:15], 0, s[4:5]
	v_or_b32_e32 v20, 1, v51
	v_addc_co_u32_e32 v17, vcc, 0, v11, vcc
	v_lshl_add_u64 v[14:15], v[14:15], 0, v[154:155]
	v_mad_i64_i32 v[20:21], s[6:7], v20, s33, v[44:45]
	v_add_co_u32_e32 v18, vcc, s46, v14
	v_lshl_add_u64 v[20:21], v[20:21], 0, s[4:5]
	s_nop 0
	v_addc_co_u32_e32 v19, vcc, 0, v15, vcc
	v_lshl_add_u64 v[20:21], v[20:21], 0, v[154:155]
	v_add_co_u32_e32 v26, vcc, s46, v20
	global_load_dwordx2 v[2:3], v[12:13], off
	global_load_dwordx2 v[10:11], v[16:17], off
	global_load_dwordx2 v[14:15], v[18:19], off
	v_addc_co_u32_e32 v27, vcc, 0, v21, vcc
	global_load_dwordx2 v[24:25], v[26:27], off
	global_load_dwordx2 v[20:21], v[12:13], off offset:2048
	global_load_dwordx2 v[22:23], v[16:17], off offset:2048
	s_nop 0
	global_load_dwordx2 v[12:13], v[18:19], off offset:2048
	global_load_dwordx2 v[16:17], v[26:27], off offset:2048
	v_or_b32_e32 v18, 2, v46
	v_mad_i64_i32 v[18:19], s[6:7], v18, s33, v[44:45]
	v_lshl_add_u64 v[18:19], v[18:19], 0, s[4:5]
	v_or_b32_e32 v26, 2, v47
	v_lshl_add_u64 v[18:19], v[18:19], 0, v[154:155]
	v_mad_i64_i32 v[26:27], s[6:7], v26, s33, v[44:45]
	v_add_co_u32_e32 v30, vcc, s46, v18
	v_lshl_add_u64 v[26:27], v[26:27], 0, s[4:5]
	v_or_b32_e32 v28, 2, v50
	v_addc_co_u32_e32 v31, vcc, 0, v19, vcc
	v_lshl_add_u64 v[26:27], v[26:27], 0, v[154:155]
	v_mad_i64_i32 v[28:29], s[6:7], v28, s33, v[44:45]
	v_add_co_u32_e32 v32, vcc, s46, v26
	v_lshl_add_u64 v[28:29], v[28:29], 0, s[4:5]
	v_or_b32_e32 v36, 2, v51
	v_addc_co_u32_e32 v33, vcc, 0, v27, vcc
	v_lshl_add_u64 v[28:29], v[28:29], 0, v[154:155]
	v_mad_i64_i32 v[36:37], s[6:7], v36, s33, v[44:45]
	v_add_co_u32_e32 v34, vcc, s46, v28
	v_lshl_add_u64 v[36:37], v[36:37], 0, s[4:5]
	s_nop 0
	v_addc_co_u32_e32 v35, vcc, 0, v29, vcc
	v_lshl_add_u64 v[36:37], v[36:37], 0, v[154:155]
	v_add_co_u32_e32 v42, vcc, s46, v36
	global_load_dwordx2 v[18:19], v[30:31], off
	global_load_dwordx2 v[26:27], v[32:33], off
	global_load_dwordx2 v[28:29], v[34:35], off
	v_addc_co_u32_e32 v43, vcc, 0, v37, vcc
	global_load_dwordx2 v[36:37], v[42:43], off
	global_load_dwordx2 v[38:39], v[30:31], off offset:2048
	global_load_dwordx2 v[40:41], v[32:33], off offset:2048
	s_nop 0
	global_load_dwordx2 v[30:31], v[34:35], off offset:2048
	global_load_dwordx2 v[32:33], v[42:43], off offset:2048
	v_or_b32_e32 v34, 3, v46
	v_mad_i64_i32 v[34:35], s[6:7], v34, s33, v[44:45]
	v_lshl_add_u64 v[34:35], v[34:35], 0, s[4:5]
	v_or_b32_e32 v42, 3, v47
	v_lshl_add_u64 v[34:35], v[34:35], 0, v[154:155]
	v_mad_i64_i32 v[42:43], s[6:7], v42, s33, v[44:45]
	v_add_co_u32_e32 v48, vcc, s46, v34
	v_lshl_add_u64 v[42:43], v[42:43], 0, s[4:5]
	v_or_b32_e32 v46, 3, v50
	v_addc_co_u32_e32 v49, vcc, 0, v35, vcc
	v_lshl_add_u64 v[42:43], v[42:43], 0, v[154:155]
	v_mad_i64_i32 v[46:47], s[6:7], v46, s33, v[44:45]
	v_add_co_u32_e32 v52, vcc, s46, v42
	v_lshl_add_u64 v[46:47], v[46:47], 0, s[4:5]
	v_or_b32_e32 v50, 3, v51
	v_addc_co_u32_e32 v53, vcc, 0, v43, vcc
	v_lshl_add_u64 v[46:47], v[46:47], 0, v[154:155]
	v_mad_i64_i32 v[44:45], s[6:7], v50, s33, v[44:45]
	v_add_co_u32_e32 v64, vcc, s46, v46
	v_lshl_add_u64 v[44:45], v[44:45], 0, s[4:5]
	global_load_dwordx2 v[34:35], v[48:49], off
	global_load_dwordx2 v[42:43], v[52:53], off
	v_addc_co_u32_e32 v65, vcc, 0, v47, vcc
	v_lshl_add_u64 v[44:45], v[44:45], 0, v[154:155]
	global_load_dwordx2 v[46:47], v[64:65], off
	v_add_co_u32_e32 v66, vcc, s46, v44
	s_lshl_b32 s6, s10, 13
	s_nop 0
	v_addc_co_u32_e32 v67, vcc, 0, v45, vcc
	global_load_dwordx2 v[54:55], v[66:67], off
	global_load_dwordx2 v[50:51], v[48:49], off offset:2048
	s_nop 0
	global_load_dwordx2 v[52:53], v[52:53], off offset:2048
	s_nop 0
	global_load_dwordx2 v[44:45], v[64:65], off offset:2048
	global_load_dwordx2 v[48:49], v[66:67], off offset:2048
	s_waitcnt vmcnt(30)
	ds_write2_b64 v102, v[56:57], v[58:59] offset1:72
	s_waitcnt vmcnt(28)
	ds_write2_b64 v102, v[60:61], v[62:63] offset0:144 offset1:216
	v_add_u32_e32 v56, 0x800, v102
	s_waitcnt vmcnt(26)
	ds_write2_b64 v56, v[0:1], v[4:5] offset0:32 offset1:104
	s_waitcnt vmcnt(24)
	ds_write2_b64 v56, v[6:7], v[8:9] offset0:176 offset1:248
	v_add_u32_e32 v0, 0x1000, v102
	s_waitcnt vmcnt(22)
	ds_write2_b64 v0, v[2:3], v[10:11] offset0:64 offset1:136
	v_add_u32_e32 v0, 0x1400, v102
	s_waitcnt vmcnt(20)
	ds_write2_b64 v0, v[14:15], v[24:25] offset0:80 offset1:152
	v_add_u32_e32 v0, 0x1800, v102
	s_waitcnt vmcnt(18)
	ds_write2_b64 v0, v[20:21], v[22:23] offset0:96 offset1:168
	v_add_u32_e32 v0, 0x1c00, v102
	s_waitcnt vmcnt(16)
	ds_write2_b64 v0, v[12:13], v[16:17] offset0:112 offset1:184
	v_add_u32_e32 v0, 0x2000, v102
	s_add_u32 s6, s3, s6
	s_addc_u32 s7, s8, 0
	v_mov_b32_e32 v87, v155
	v_mov_b32_e32 v89, v155
	v_mov_b32_e32 v91, v155
	s_add_u32 s22, s6, 0x1000
	s_addc_u32 s23, s7, 0
	v_lshl_add_u64 v[92:93], v[84:85], 0, s[4:5]
	s_waitcnt vmcnt(14)
	ds_write2_b64 v0, v[18:19], v[26:27] offset0:128 offset1:200
	v_add_u32_e32 v0, 0x2800, v102
	s_waitcnt vmcnt(12)
	ds_write2_b64 v0, v[28:29], v[36:37] offset0:16 offset1:88
	s_waitcnt vmcnt(10)
	ds_write2_b64 v0, v[38:39], v[40:41] offset0:160 offset1:232
	v_add_u32_e32 v0, 0x3000, v102
	s_waitcnt vmcnt(8)
	ds_write2_b64 v0, v[30:31], v[32:33] offset0:48 offset1:120
	v_add_u32_e32 v0, 0x3400, v102
	v_lshl_add_u64 v[32:33], s[6:7], 0, v[86:87]
	v_lshl_add_u64 v[32:33], v[32:33], 0, v[88:89]
	s_waitcnt vmcnt(6)
	ds_write2_b64 v0, v[34:35], v[42:43] offset0:64 offset1:136
	v_add_u32_e32 v0, 0x3800, v102
	v_lshl_add_u64 v[34:35], s[6:7], 0, v[90:91]
	v_lshl_add_u64 v[34:35], v[34:35], 0, v[88:89]
	s_add_u32 s6, s6, 0x1800
	s_addc_u32 s7, s7, 0
	s_waitcnt vmcnt(4)
	ds_write2_b64 v0, v[46:47], v[54:55] offset0:80 offset1:152
	v_add_u32_e32 v0, 0x3c00, v102
	s_waitcnt vmcnt(2)
	ds_write2_b64 v0, v[50:51], v[52:53] offset0:96 offset1:168
	v_add_u32_e32 v0, 0x4000, v102
	s_waitcnt vmcnt(0)
	ds_write2_b64 v0, v[44:45], v[48:49] offset0:112 offset1:184
	ds_read_b64_tr_b16 v[62:63], v94 offset:2304
	ds_read_b64_tr_b16 v[60:61], v94
	ds_read_b64_tr_b16 v[64:65], v94 offset:32
	ds_read_b64_tr_b16 v[66:67], v94 offset:2336
	ds_read_b64_tr_b16 v[68:69], v94 offset:64
	ds_read_b64_tr_b16 v[70:71], v94 offset:2368
	ds_read_b64_tr_b16 v[72:73], v94 offset:96
	ds_read_b64_tr_b16 v[74:75], v94 offset:2400
	ds_read_b64_tr_b16 v[36:37], v94 offset:4608
	ds_read_b64_tr_b16 v[38:39], v94 offset:6912
	ds_read_b64_tr_b16 v[40:41], v94 offset:4640
	ds_read_b64_tr_b16 v[42:43], v94 offset:6944
	ds_read_b64_tr_b16 v[44:45], v94 offset:4672
	ds_read_b64_tr_b16 v[46:47], v94 offset:6976
	ds_read_b64_tr_b16 v[48:49], v94 offset:4704
	ds_read_b64_tr_b16 v[50:51], v94 offset:7008
	ds_read_b64_tr_b16 v[16:17], v94 offset:9216
	ds_read_b64_tr_b16 v[18:19], v94 offset:11520
	ds_read_b64_tr_b16 v[20:21], v94 offset:9248
	ds_read_b64_tr_b16 v[22:23], v94 offset:11552
	ds_read_b64_tr_b16 v[24:25], v94 offset:9280
	ds_read_b64_tr_b16 v[26:27], v94 offset:11584
	ds_read_b64_tr_b16 v[28:29], v94 offset:9312
	ds_read_b64_tr_b16 v[30:31], v94 offset:11616
	ds_read_b64_tr_b16 v[0:1], v94 offset:13824
	ds_read_b64_tr_b16 v[2:3], v94 offset:16128
	ds_read_b64_tr_b16 v[4:5], v94 offset:13856
	ds_read_b64_tr_b16 v[6:7], v94 offset:16160
	ds_read_b64_tr_b16 v[8:9], v94 offset:13888
	ds_read_b64_tr_b16 v[10:11], v94 offset:16192
	ds_read_b64_tr_b16 v[12:13], v94 offset:13920
	ds_read_b64_tr_b16 v[14:15], v94 offset:16224
	global_load_dwordx2 v[104:105], v[32:33], off
	global_load_dwordx2 v[106:107], v[32:33], off offset:32
	global_load_dwordx2 v[108:109], v[34:35], off
	global_load_dwordx2 v[110:111], v[34:35], off offset:32
	global_load_dwordx2 v[112:113], v[32:33], off offset:2048
	global_load_dwordx2 v[114:115], v[32:33], off offset:2080
	global_load_dwordx2 v[80:81], v[34:35], off offset:2048
	global_load_dwordx2 v[82:83], v[34:35], off offset:2080
	v_lshl_add_u64 v[32:33], s[22:23], 0, v[86:87]
	v_lshl_add_u64 v[32:33], v[32:33], 0, v[88:89]
	global_load_dwordx2 v[76:77], v[32:33], off
	global_load_dwordx2 v[78:79], v[32:33], off offset:32
	v_lshl_add_u64 v[32:33], s[22:23], 0, v[90:91]
	v_lshl_add_u64 v[32:33], v[32:33], 0, v[88:89]
	global_load_dwordx2 v[56:57], v[32:33], off
	global_load_dwordx2 v[58:59], v[32:33], off offset:32
	v_lshl_add_u64 v[32:33], s[6:7], 0, v[86:87]
	v_lshl_add_u64 v[32:33], v[32:33], 0, v[88:89]
	global_load_dwordx2 v[52:53], v[32:33], off
	global_load_dwordx2 v[54:55], v[32:33], off offset:32
	v_lshl_add_u64 v[32:33], s[6:7], 0, v[90:91]
	v_lshl_add_u64 v[34:35], v[32:33], 0, v[88:89]
	global_load_dwordx2 v[32:33], v[34:35], off
	s_nop 0
	global_load_dwordx2 v[34:35], v[34:35], off offset:32
	s_lshl_b32 s6, s11, 4
	v_or_b32_e32 v89, s6, v100
	v_lshl_or_b32 v87, s10, 3, v95
	s_waitcnt vmcnt(14) lgkmcnt(14)
	v_mfma_f32_16x16x32_bf16 v[116:119], v[60:63], v[104:107], 0
	v_lshl_add_u32 v89, v89, 8, v89
	v_add_u32_e32 v128, v87, v89
	v_ashrrev_i32_e32 v129, 31, v128
	v_mfma_f32_16x16x32_bf16 v[120:123], v[64:67], v[104:107], 0
	v_lshlrev_b64 v[128:129], 11, v[128:129]
	v_lshl_add_u64 v[128:129], v[92:93], 0, v[128:129]
	s_nop 1
	v_cvt_pk_bf16_f32 v116, v116, v117
	v_mfma_f32_16x16x32_bf16 v[124:127], v[68:71], v[104:107], 0
	v_cvt_pk_bf16_f32 v117, v118, v119
	ds_write_b64 v216, v[116:117]
	v_cvt_pk_bf16_f32 v116, v120, v121
	v_mfma_f32_16x16x32_bf16 v[104:107], v[72:75], v[104:107], 0
	v_cvt_pk_bf16_f32 v117, v122, v123
	ds_write_b64 v216, v[116:117] offset:32
	s_nop 1
	v_cvt_pk_bf16_f32 v116, v124, v125
	v_cvt_pk_bf16_f32 v117, v126, v127
	ds_write_b64 v216, v[116:117] offset:64
	s_nop 0
	v_cvt_pk_bf16_f32 v104, v104, v105
	v_cvt_pk_bf16_f32 v105, v106, v107
	ds_write_b64 v216, v[104:105] offset:96
	v_readfirstlane_b32 s98, v128
	v_readfirstlane_b32 s99, v129
	ds_read_b64 v[220:221], v217
	ds_read_b64 v[222:223], v217 offset:576
	ds_read_b64 v[224:225], v217 offset:1152
	ds_read_b64 v[226:227], v217 offset:1728
	s_waitcnt lgkmcnt(3)
	global_store_dwordx2 v218, v[220:221], s[98:99]
	s_waitcnt lgkmcnt(2)
	global_store_dwordx2 v219, v[222:223], s[98:99]
	s_waitcnt lgkmcnt(1)
	global_store_dwordx2 v228, v[224:225], s[98:99]
	s_waitcnt lgkmcnt(0)
	global_store_dwordx2 v229, v[226:227], s[98:99]
	s_waitcnt vmcnt(16)
	v_mfma_f32_16x16x32_bf16 v[104:107], v[60:63], v[108:111], 0
	v_or_b32_e32 v60, s6, v101
	v_lshl_add_u32 v60, v60, 8, v60
	v_or_b32_e32 v61, 2, v87
	v_mfma_f32_16x16x32_bf16 v[62:65], v[64:67], v[108:111], 0
	s_add_i32 s9, s9, s28
	s_nop 2
	v_cvt_pk_bf16_f32 v104, v104, v105
	v_cvt_pk_bf16_f32 v105, v106, v107
	v_mfma_f32_16x16x32_bf16 v[66:69], v[68:71], v[108:111], 0
	s_add_i32 s2, s2, s12
	v_cvt_pk_bf16_f32 v62, v62, v63
	v_cvt_pk_bf16_f32 v63, v64, v65
	v_mfma_f32_16x16x32_bf16 v[70:73], v[72:75], v[108:111], 0
	v_add_u32_e32 v74, v87, v60
	v_ashrrev_i32_e32 v75, 31, v74
	v_lshlrev_b64 v[74:75], 11, v[74:75]
	v_lshl_add_u64 v[74:75], v[92:93], 0, v[74:75]
	ds_write_b64 v216, v[62:63] offset:32
	v_cvt_pk_bf16_f32 v62, v66, v67
	v_cvt_pk_bf16_f32 v63, v68, v69
	ds_write_b64 v216, v[62:63] offset:64
	v_cvt_pk_bf16_f32 v62, v70, v71
	v_cvt_pk_bf16_f32 v63, v72, v73
	ds_write_b64 v216, v[62:63] offset:96
	s_waitcnt vmcnt(14)
	v_mfma_f32_16x16x32_bf16 v[62:65], v[36:39], v[112:115], 0
	ds_write_b64 v216, v[104:105]
	v_readfirstlane_b32 s98, v74
	v_readfirstlane_b32 s99, v75
	ds_read_b64 v[220:221], v217
	ds_read_b64 v[222:223], v217 offset:576
	ds_read_b64 v[224:225], v217 offset:1152
	ds_read_b64 v[226:227], v217 offset:1728
	s_waitcnt lgkmcnt(3)
	global_store_dwordx2 v218, v[220:221], s[98:99]
	s_waitcnt lgkmcnt(2)
	global_store_dwordx2 v219, v[222:223], s[98:99]
	s_waitcnt lgkmcnt(1)
	global_store_dwordx2 v228, v[224:225], s[98:99]
	s_waitcnt lgkmcnt(0)
	global_store_dwordx2 v229, v[226:227], s[98:99]
	v_add_u32_e32 v74, v61, v89
	v_ashrrev_i32_e32 v75, 31, v74
	v_mfma_f32_16x16x32_bf16 v[66:69], v[40:43], v[112:115], 0
	v_lshlrev_b64 v[74:75], 11, v[74:75]
	v_lshl_add_u64 v[74:75], v[92:93], 0, v[74:75]
	s_nop 1
	v_cvt_pk_bf16_f32 v62, v62, v63
	v_mfma_f32_16x16x32_bf16 v[70:73], v[44:47], v[112:115], 0
	v_cvt_pk_bf16_f32 v63, v64, v65
	ds_write_b64 v216, v[62:63]
	v_cvt_pk_bf16_f32 v62, v66, v67
	v_mfma_f32_16x16x32_bf16 v[104:107], v[48:51], v[112:115], 0
	v_cvt_pk_bf16_f32 v63, v68, v69
	ds_write_b64 v216, v[62:63] offset:32
	s_nop 1
	v_cvt_pk_bf16_f32 v62, v70, v71
	v_cvt_pk_bf16_f32 v63, v72, v73
	ds_write_b64 v216, v[62:63] offset:64
	s_nop 0
	v_cvt_pk_bf16_f32 v62, v104, v105
	v_cvt_pk_bf16_f32 v63, v106, v107
	s_waitcnt vmcnt(16)
	v_mfma_f32_16x16x32_bf16 v[36:39], v[36:39], v[80:83], 0
	ds_write_b64 v216, v[62:63] offset:96
	v_readfirstlane_b32 s98, v74
	v_readfirstlane_b32 s99, v75
	ds_read_b64 v[220:221], v217
	ds_read_b64 v[222:223], v217 offset:576
	ds_read_b64 v[224:225], v217 offset:1152
	ds_read_b64 v[226:227], v217 offset:1728
	s_waitcnt lgkmcnt(3)
	global_store_dwordx2 v218, v[220:221], s[98:99]
	s_waitcnt lgkmcnt(2)
	global_store_dwordx2 v219, v[222:223], s[98:99]
	s_waitcnt lgkmcnt(1)
	global_store_dwordx2 v228, v[224:225], s[98:99]
	s_waitcnt lgkmcnt(0)
	global_store_dwordx2 v229, v[226:227], s[98:99]
	v_add_u32_e32 v62, v61, v60
	v_ashrrev_i32_e32 v63, 31, v62
	v_mfma_f32_16x16x32_bf16 v[40:43], v[40:43], v[80:83], 0
	v_lshlrev_b64 v[62:63], 11, v[62:63]
	v_lshl_add_u64 v[62:63], v[92:93], 0, v[62:63]
	s_nop 1
	v_cvt_pk_bf16_f32 v36, v36, v37
	v_mfma_f32_16x16x32_bf16 v[44:47], v[44:47], v[80:83], 0
	v_cvt_pk_bf16_f32 v37, v38, v39
	ds_write_b64 v216, v[36:37]
	v_cvt_pk_bf16_f32 v36, v40, v41
	v_mfma_f32_16x16x32_bf16 v[48:51], v[48:51], v[80:83], 0
	v_cvt_pk_bf16_f32 v37, v42, v43
	ds_write_b64 v216, v[36:37] offset:32
	s_nop 1
	v_cvt_pk_bf16_f32 v36, v44, v45
	v_cvt_pk_bf16_f32 v37, v46, v47
	ds_write_b64 v216, v[36:37] offset:64
	s_nop 0
	v_cvt_pk_bf16_f32 v36, v48, v49
	v_cvt_pk_bf16_f32 v37, v50, v51
	ds_write_b64 v216, v[36:37] offset:96
	v_readfirstlane_b32 s98, v62
	v_readfirstlane_b32 s99, v63
	ds_read_b64 v[220:221], v217
	ds_read_b64 v[222:223], v217 offset:576
	ds_read_b64 v[224:225], v217 offset:1152
	ds_read_b64 v[226:227], v217 offset:1728
	s_waitcnt lgkmcnt(3)
	global_store_dwordx2 v218, v[220:221], s[98:99]
	s_waitcnt lgkmcnt(2)
	global_store_dwordx2 v219, v[222:223], s[98:99]
	s_waitcnt lgkmcnt(1)
	global_store_dwordx2 v228, v[224:225], s[98:99]
	s_waitcnt lgkmcnt(0)
	global_store_dwordx2 v229, v[226:227], s[98:99]
	s_waitcnt vmcnt(22)
	v_mfma_f32_16x16x32_bf16 v[36:39], v[16:19], v[76:79], 0
	v_or_b32_e32 v61, 4, v87
	v_add_u32_e32 v62, v61, v89
	v_ashrrev_i32_e32 v63, 31, v62
	s_waitcnt lgkmcnt(12)
	v_mfma_f32_16x16x32_bf16 v[40:43], v[20:23], v[76:79], 0
	v_lshlrev_b64 v[62:63], 11, v[62:63]
	v_lshl_add_u64 v[62:63], v[92:93], 0, v[62:63]
	s_nop 0
	v_cvt_pk_bf16_f32 v36, v36, v37
	s_waitcnt lgkmcnt(10)
	v_mfma_f32_16x16x32_bf16 v[44:47], v[24:27], v[76:79], 0
	v_cvt_pk_bf16_f32 v37, v38, v39
	ds_write_b64 v216, v[36:37]
	v_cvt_pk_bf16_f32 v36, v40, v41
	s_waitcnt lgkmcnt(8)
	v_mfma_f32_16x16x32_bf16 v[48:51], v[28:31], v[76:79], 0
	v_cvt_pk_bf16_f32 v37, v42, v43
	ds_write_b64 v216, v[36:37] offset:32
	s_nop 0
	v_cvt_pk_bf16_f32 v36, v44, v45
	v_cvt_pk_bf16_f32 v37, v46, v47
	ds_write_b64 v216, v[36:37] offset:64
	s_nop 1
	v_cvt_pk_bf16_f32 v36, v48, v49
	v_cvt_pk_bf16_f32 v37, v50, v51
	s_waitcnt vmcnt(20)
	v_mfma_f32_16x16x32_bf16 v[16:19], v[16:19], v[56:59], 0
	ds_write_b64 v216, v[36:37] offset:96
	v_readfirstlane_b32 s98, v62
	v_readfirstlane_b32 s99, v63
	ds_read_b64 v[220:221], v217
	ds_read_b64 v[222:223], v217 offset:576
	ds_read_b64 v[224:225], v217 offset:1152
	ds_read_b64 v[226:227], v217 offset:1728
	s_waitcnt lgkmcnt(3)
	global_store_dwordx2 v218, v[220:221], s[98:99]
	s_waitcnt lgkmcnt(2)
	global_store_dwordx2 v219, v[222:223], s[98:99]
	s_waitcnt lgkmcnt(1)
	global_store_dwordx2 v228, v[224:225], s[98:99]
	s_waitcnt lgkmcnt(0)
	global_store_dwordx2 v229, v[226:227], s[98:99]
	v_add_u32_e32 v36, v61, v60
	v_ashrrev_i32_e32 v37, 31, v36
	v_mfma_f32_16x16x32_bf16 v[20:23], v[20:23], v[56:59], 0
	v_lshlrev_b64 v[36:37], 11, v[36:37]
	v_lshl_add_u64 v[36:37], v[92:93], 0, v[36:37]
	s_nop 1
	v_cvt_pk_bf16_f32 v16, v16, v17
	v_mfma_f32_16x16x32_bf16 v[24:27], v[24:27], v[56:59], 0
	v_cvt_pk_bf16_f32 v17, v18, v19
	ds_write_b64 v216, v[16:17]
	v_cvt_pk_bf16_f32 v16, v20, v21
	v_mfma_f32_16x16x32_bf16 v[28:31], v[28:31], v[56:59], 0
	v_cvt_pk_bf16_f32 v17, v22, v23
	ds_write_b64 v216, v[16:17] offset:32
	s_nop 1
	v_cvt_pk_bf16_f32 v16, v24, v25
	v_cvt_pk_bf16_f32 v17, v26, v27
	ds_write_b64 v216, v[16:17] offset:64
	s_nop 0
	v_cvt_pk_bf16_f32 v16, v28, v29
	v_cvt_pk_bf16_f32 v17, v30, v31
	ds_write_b64 v216, v[16:17] offset:96
	v_readfirstlane_b32 s98, v36
	v_readfirstlane_b32 s99, v37
	ds_read_b64 v[220:221], v217
	ds_read_b64 v[222:223], v217 offset:576
	ds_read_b64 v[224:225], v217 offset:1152
	ds_read_b64 v[226:227], v217 offset:1728
	s_waitcnt lgkmcnt(3)
	global_store_dwordx2 v218, v[220:221], s[98:99]
	s_waitcnt lgkmcnt(2)
	global_store_dwordx2 v219, v[222:223], s[98:99]
	s_waitcnt lgkmcnt(1)
	global_store_dwordx2 v228, v[224:225], s[98:99]
	s_waitcnt lgkmcnt(0)
	global_store_dwordx2 v229, v[226:227], s[98:99]
	s_waitcnt vmcnt(26) lgkmcnt(6)
	v_mfma_f32_16x16x32_bf16 v[16:19], v[0:3], v[52:55], 0
	v_or_b32_e32 v38, 6, v87
	v_add_u32_e32 v36, v38, v89
	v_ashrrev_i32_e32 v37, 31, v36
	s_waitcnt lgkmcnt(4)
	v_mfma_f32_16x16x32_bf16 v[20:23], v[4:7], v[52:55], 0
	v_lshlrev_b64 v[36:37], 11, v[36:37]
	v_lshl_add_u64 v[36:37], v[92:93], 0, v[36:37]
	s_nop 0
	v_cvt_pk_bf16_f32 v16, v16, v17
	s_waitcnt lgkmcnt(2)
	v_mfma_f32_16x16x32_bf16 v[24:27], v[8:11], v[52:55], 0
	v_cvt_pk_bf16_f32 v17, v18, v19
	ds_write_b64 v216, v[16:17]
	v_cvt_pk_bf16_f32 v16, v20, v21
	s_waitcnt lgkmcnt(0)
	v_mfma_f32_16x16x32_bf16 v[28:31], v[12:15], v[52:55], 0
	v_cvt_pk_bf16_f32 v17, v22, v23
	ds_write_b64 v216, v[16:17] offset:32
	s_nop 0
	v_cvt_pk_bf16_f32 v16, v24, v25
	v_cvt_pk_bf16_f32 v17, v26, v27
	ds_write_b64 v216, v[16:17] offset:64
	s_nop 1
	v_cvt_pk_bf16_f32 v16, v28, v29
	v_cvt_pk_bf16_f32 v17, v30, v31
	s_waitcnt vmcnt(24)
	v_mfma_f32_16x16x32_bf16 v[0:3], v[0:3], v[32:35], 0
	ds_write_b64 v216, v[16:17] offset:96
	v_readfirstlane_b32 s98, v36
	v_readfirstlane_b32 s99, v37
	ds_read_b64 v[220:221], v217
	ds_read_b64 v[222:223], v217 offset:576
	ds_read_b64 v[224:225], v217 offset:1152
	ds_read_b64 v[226:227], v217 offset:1728
	s_waitcnt lgkmcnt(3)
	global_store_dwordx2 v218, v[220:221], s[98:99]
	s_waitcnt lgkmcnt(2)
	global_store_dwordx2 v219, v[222:223], s[98:99]
	s_waitcnt lgkmcnt(1)
	global_store_dwordx2 v228, v[224:225], s[98:99]
	s_waitcnt lgkmcnt(0)
	global_store_dwordx2 v229, v[226:227], s[98:99]
	v_add_u32_e32 v16, v38, v60
	v_ashrrev_i32_e32 v17, 31, v16
	v_mfma_f32_16x16x32_bf16 v[4:7], v[4:7], v[32:35], 0
	v_lshlrev_b64 v[16:17], 11, v[16:17]
	v_lshl_add_u64 v[16:17], v[92:93], 0, v[16:17]
	s_nop 1
	v_cvt_pk_bf16_f32 v0, v0, v1
	v_mfma_f32_16x16x32_bf16 v[8:11], v[8:11], v[32:35], 0
	v_cvt_pk_bf16_f32 v1, v2, v3
	ds_write_b64 v216, v[0:1]
	v_cvt_pk_bf16_f32 v0, v4, v5
	v_mfma_f32_16x16x32_bf16 v[12:15], v[12:15], v[32:35], 0
	v_cvt_pk_bf16_f32 v1, v6, v7
	ds_write_b64 v216, v[0:1] offset:32
	s_nop 1
	v_cvt_pk_bf16_f32 v0, v8, v9
	v_cvt_pk_bf16_f32 v1, v10, v11
	ds_write_b64 v216, v[0:1] offset:64
	s_nop 0
	v_cvt_pk_bf16_f32 v0, v12, v13
	v_cvt_pk_bf16_f32 v1, v14, v15
	ds_write_b64 v216, v[0:1] offset:96
	v_readfirstlane_b32 s98, v16
	v_readfirstlane_b32 s99, v17
	ds_read_b64 v[220:221], v217
	ds_read_b64 v[222:223], v217 offset:576
	ds_read_b64 v[224:225], v217 offset:1152
	ds_read_b64 v[226:227], v217 offset:1728
	s_waitcnt lgkmcnt(3)
	global_store_dwordx2 v218, v[220:221], s[98:99]
	s_waitcnt lgkmcnt(2)
	global_store_dwordx2 v219, v[222:223], s[98:99]
	s_waitcnt lgkmcnt(1)
	global_store_dwordx2 v228, v[224:225], s[98:99]
	s_waitcnt lgkmcnt(0)
	global_store_dwordx2 v229, v[226:227], s[98:99]
	s_cmpk_gt_i32 s9, 0xfff
	s_cbranch_scc0 .LBB0_134
